# strategy 7.3: attention epilogues (MLA+dilated) 16 dwordx2 stores -> 8 dwordx4 via v_permlane32_swap pairs, on top of v3
# speedup vs baseline: 1.0027x; 1.0002x over previous
; __device__ __forceinline__ unsigned pk2(float lo, float hi) { return pg8::cvt_pk_bf16(lo, hi); }
; template <int DQK, bool HAS_LSE>
; __device__ __forceinline__ void unit(LAS unsigned char* lds, const Desc& d) {
;     ...
;     int tid_e = threadIdx.x; asm volatile("" : "+v"(tid_e));
;     const int r_e = tid_e & 31, hi_e = (tid_e >> 5) & 1;
;     l += __shfl_xor(l, 32);
;     const float inv = 1.0f / l;
;     bf16* op = d.O + (long)(32 * w + r_e) * d.os + 4 * hi_e;
; #pragma unroll
;     for (int db = 0; db < 4; ++db)
; #pragma unroll
;         for (int g = 0; g < 4; ++g) { v2u wv; wv.x = pk2(o[db][4 * g] * inv, o[db][4 * g + 1] * inv); wv.y = pk2(o[db][4 * g + 2] * inv, o[db][4 * g + 3] * inv); *(v2u*)(op + 32 * db + 8 * g) = wv; }
;     if (HAS_LSE) { if (hi_e == 0) d.LSE[(long)(32 * w + r_e) * d.lses] = m + __builtin_amdgcn_logf(l); }
.LBB0_530:
	s_ashr_i32 s7, s6, 31
	s_lshl_b32 s4, s47, 7
	s_lshl_b64 s[14:15], s[6:7], 25
	v_cmp_lt_i32_e32 vcc, v218, v212
	s_add_u32 s5, s3, s14
	s_addc_u32 s14, s33, s15
	v_cndmask_b32_e32 v0, v211, v218, vcc
	v_lshlrev_b32_e32 v0, 2, v0
	s_cmp_lt_i32 s6, 2
	v_readlane_b32 s15, v253, 27
	ds_bpermute_b32 v0, v0, v66
	s_cselect_b32 s22, s14, s15
	v_readlane_b32 s14, v253, 26
	s_cselect_b32 s5, s5, s14
	s_lshl_b64 s[14:15], s[8:9], 11
	s_add_u32 s5, s5, s14
	s_addc_u32 s14, s22, s15
	s_lshl_b32 s4, s4, 1
	s_add_u32 s4, s5, s4
	s_waitcnt lgkmcnt(0)
	v_add_f32_e32 v68, v66, v0
	s_addc_u32 s5, s14, 0
	v_div_scale_f32 v0, s[14:15], v68, v68, 1.0
	v_rcp_f32_e32 v66, v0
	v_mov_b32_e32 v67, v204
	s_add_i32 s14, s21, 10
	v_fma_f32 v70, -v0, v66, 1.0
	v_fmac_f32_e32 v66, v70, v66
	v_div_scale_f32 v70, vcc, 1.0, v68, 1.0
	v_mul_f32_e32 v71, v70, v66
	v_fma_f32 v72, -v0, v71, v70
	v_fmac_f32_e32 v71, v72, v66
	v_fma_f32 v0, -v0, v71, v70
	v_div_fmas_f32 v0, v0, v66, v71
	v_and_or_b32 v66, v67, 31, s56
	v_bfe_u32 v69, v67, 5, 1
	v_ashrrev_i32_e32 v67, 31, v66
	v_lshlrev_b64 v[70:71], s14, v[66:67]
	v_div_fixup_f32 v72, v0, v68, 1.0
	v_lshl_add_u64 v[70:71], v[70:71], 1, s[4:5]
	v_lshlrev_b32_e32 v0, 3, v69
	v_lshl_add_u64 v[70:71], v[70:71], 0, v[0:1]
	v_lshl_add_u64 v[70:71], v[70:71], 0, v[0:1]
	v_mul_f32_e32 v0, v50, v72
	v_mul_f32_e32 v50, v51, v72
	v_cvt_pk_bf16_f32 v50, v0, v50
	v_mul_f32_e32 v0, v52, v72
	v_mul_f32_e32 v51, v53, v72
	v_cvt_pk_bf16_f32 v51, v0, v51
	v_mul_f32_e32 v0, v54, v72
	v_mul_f32_e32 v52, v55, v72
	v_cvt_pk_bf16_f32 v52, v0, v52
	v_mul_f32_e32 v0, v56, v72
	v_mul_f32_e32 v53, v57, v72
	v_cvt_pk_bf16_f32 v53, v0, v53
	s_nop 1
	v_permlane32_swap_b32_e32 v50, v52
	v_permlane32_swap_b32_e32 v51, v53
	global_store_dwordx4 v[70:71], v[50:53], off
	v_mul_f32_e32 v0, v58, v72
	v_mul_f32_e32 v58, v59, v72
	v_cvt_pk_bf16_f32 v58, v0, v58
	v_mul_f32_e32 v0, v60, v72
	v_mul_f32_e32 v59, v61, v72
	v_cvt_pk_bf16_f32 v59, v0, v59
	v_mul_f32_e32 v0, v62, v72
	v_mul_f32_e32 v60, v63, v72
	v_cvt_pk_bf16_f32 v60, v0, v60
	v_mul_f32_e32 v0, v64, v72
	v_mul_f32_e32 v61, v65, v72
	v_cvt_pk_bf16_f32 v61, v0, v61
	s_nop 1
	v_permlane32_swap_b32_e32 v58, v60
	v_permlane32_swap_b32_e32 v59, v61
	global_store_dwordx4 v[70:71], v[58:61], off offset:32
	v_mul_f32_e32 v0, v34, v72
	v_mul_f32_e32 v34, v35, v72
	v_cvt_pk_bf16_f32 v34, v0, v34
	v_mul_f32_e32 v0, v36, v72
	v_mul_f32_e32 v35, v37, v72
	v_cvt_pk_bf16_f32 v35, v0, v35
	v_mul_f32_e32 v0, v38, v72
	v_mul_f32_e32 v36, v39, v72
	v_cvt_pk_bf16_f32 v36, v0, v36
	v_mul_f32_e32 v0, v40, v72
	v_mul_f32_e32 v37, v41, v72
	v_cvt_pk_bf16_f32 v37, v0, v37
	s_nop 1
	v_permlane32_swap_b32_e32 v34, v36
	v_permlane32_swap_b32_e32 v35, v37
	global_store_dwordx4 v[70:71], v[34:37], off offset:64
	v_mul_f32_e32 v0, v42, v72
	v_mul_f32_e32 v42, v43, v72
	v_cvt_pk_bf16_f32 v42, v0, v42
	v_mul_f32_e32 v0, v44, v72
	v_mul_f32_e32 v43, v45, v72
	v_cvt_pk_bf16_f32 v43, v0, v43
	v_mul_f32_e32 v0, v46, v72
	v_mul_f32_e32 v44, v47, v72
	v_cvt_pk_bf16_f32 v44, v0, v44
	v_mul_f32_e32 v0, v48, v72
	v_mul_f32_e32 v45, v49, v72
	v_cvt_pk_bf16_f32 v45, v0, v45
	s_nop 1
	v_permlane32_swap_b32_e32 v42, v44
	v_permlane32_swap_b32_e32 v43, v45
	global_store_dwordx4 v[70:71], v[42:45], off offset:96
	v_mul_f32_e32 v0, v18, v72
	v_mul_f32_e32 v18, v19, v72
	v_cvt_pk_bf16_f32 v18, v0, v18
	v_mul_f32_e32 v0, v20, v72
	v_mul_f32_e32 v19, v21, v72
	v_cvt_pk_bf16_f32 v19, v0, v19
	v_mul_f32_e32 v0, v22, v72
	v_mul_f32_e32 v20, v23, v72
	v_cvt_pk_bf16_f32 v20, v0, v20
	v_mul_f32_e32 v0, v24, v72
	v_mul_f32_e32 v21, v25, v72
	v_cvt_pk_bf16_f32 v21, v0, v21
	s_nop 1
	v_permlane32_swap_b32_e32 v18, v20
	v_permlane32_swap_b32_e32 v19, v21
	global_store_dwordx4 v[70:71], v[18:21], off offset:128
	v_mul_f32_e32 v0, v26, v72
	v_mul_f32_e32 v26, v27, v72
	v_cvt_pk_bf16_f32 v26, v0, v26
	v_mul_f32_e32 v0, v28, v72
	v_mul_f32_e32 v27, v29, v72
	v_cvt_pk_bf16_f32 v27, v0, v27
	v_mul_f32_e32 v0, v30, v72
	v_mul_f32_e32 v28, v31, v72
	v_cvt_pk_bf16_f32 v28, v0, v28
	v_mul_f32_e32 v0, v32, v72
	v_mul_f32_e32 v29, v33, v72
	v_cvt_pk_bf16_f32 v29, v0, v29
	v_cmp_eq_u32_e32 vcc, 0, v69
	s_nop 1
	v_permlane32_swap_b32_e32 v26, v28
	v_permlane32_swap_b32_e32 v27, v29
	global_store_dwordx4 v[70:71], v[26:29], off offset:160
	v_mul_f32_e32 v0, v2, v72
	v_mul_f32_e32 v2, v3, v72
	v_cvt_pk_bf16_f32 v2, v0, v2
	v_mul_f32_e32 v0, v4, v72
	v_mul_f32_e32 v3, v5, v72
	v_cvt_pk_bf16_f32 v3, v0, v3
	v_mul_f32_e32 v0, v6, v72
	v_mul_f32_e32 v4, v7, v72
	v_cvt_pk_bf16_f32 v4, v0, v4
	v_mul_f32_e32 v0, v8, v72
	v_mul_f32_e32 v5, v9, v72
	v_cvt_pk_bf16_f32 v5, v0, v5
	s_nop 1
	v_permlane32_swap_b32_e32 v2, v4
	v_permlane32_swap_b32_e32 v3, v5
	global_store_dwordx4 v[70:71], v[2:5], off offset:192
	v_mul_f32_e32 v0, v10, v72
	v_mul_f32_e32 v10, v11, v72
	v_cvt_pk_bf16_f32 v10, v0, v10
	v_mul_f32_e32 v0, v12, v72
	v_mul_f32_e32 v11, v13, v72
	v_cvt_pk_bf16_f32 v11, v0, v11
	v_mul_f32_e32 v0, v14, v72
	v_mul_f32_e32 v12, v15, v72
	v_cvt_pk_bf16_f32 v12, v0, v12
	v_mul_f32_e32 v0, v16, v72
	v_mul_f32_e32 v13, v17, v72
	v_cvt_pk_bf16_f32 v13, v0, v13
	s_nop 1
	v_permlane32_swap_b32_e32 v10, v12
	v_permlane32_swap_b32_e32 v11, v13
	global_store_dwordx4 v[70:71], v[10:13], off offset:224
	s_and_saveexec_b64 s[40:41], vcc
	s_cbranch_execz .LBB0_508
	s_lshl_b64 s[4:5], s[6:7], 19
	v_readlane_b32 s6, v253, 28
	s_add_u32 s6, s6, s4
	v_readlane_b32 s4, v253, 29
	s_addc_u32 s7, s4, s5
	s_lshl_b64 s[4:5], s[8:9], 5
	s_add_u32 s4, s6, s4
	s_addc_u32 s5, s7, s5
	v_log_f32_e32 v0, v68
	s_lshl_b32 s6, s47, 2
	s_add_u32 s4, s4, s6
	s_addc_u32 s5, s5, 0
	s_add_i32 s21, s21, 3
	v_lshlrev_b64 v[2:3], s21, v[66:67]
	v_add_f32_e32 v0, v153, v0
	v_lshl_add_u64 v[2:3], v[2:3], 2, s[4:5]
	global_store_dword v[2:3], v0, off
	s_branch .LBB0_508

; __device__ __forceinline__ unsigned pk2(float lo, float hi) { return pg8::cvt_pk_bf16(lo, hi); }
; #define FA_WAIT_NI() do { if constexpr (NI == 5) asm volatile("s_waitcnt vmcnt(5)" ::: "memory"); else asm volatile("s_waitcnt vmcnt(4)" ::: "memory"); } while (0)
; template <int DQK, bool HAS_LSE>
; __device__ __forceinline__ void unit(LAS unsigned char* lds, const Desc& d) {
;     ...
;         if (pre) FA_WAIT_NI(); else asm volatile("s_waitcnt vmcnt(0)" ::: "memory");
;         asm volatile("s_waitcnt lgkmcnt(0)" ::: "memory");
;         __builtin_amdgcn_s_barrier();
;         slot = (slot == 2) ? 0 : slot + 1;
;     }
;     int tid_e = threadIdx.x; asm volatile("" : "+v"(tid_e));
;     const int r_e = tid_e & 31, hi_e = (tid_e >> 5) & 1;
;     l += __shfl_xor(l, 32);
;     const float inv = 1.0f / l;
;     bf16* op = d.O + (long)(32 * w + r_e) * d.os + 4 * hi_e;
; #pragma unroll
;     for (int db = 0; db < 4; ++db)
; #pragma unroll
;         for (int g = 0; g < 4; ++g) { v2u wv; wv.x = pk2(o[db][4 * g] * inv, o[db][4 * g + 1] * inv); wv.y = pk2(o[db][4 * g + 2] * inv, o[db][4 * g + 3] * inv); *(v2u*)(op + 32 * db + 8 * g) = wv; }
.LBB0_2004:
	s_add_i32 s4, s45, 1
	s_cmp_lg_u32 s45, 2
	s_cselect_b32 s45, s4, 0
	s_add_i32 s44, s44, 64
	s_add_u32 s53, s53, 0x20000
	s_addc_u32 s56, s56, 0
	s_waitcnt lgkmcnt(0)
	s_add_u32 s57, s57, 0x80000
	s_addc_u32 s58, s58, 0
	s_add_i32 s65, s65, 1
	s_mov_b64 s[4:5], 0x80000
	v_subrev_u32_e32 v184, 64, v184
	s_cmp_lg_u32 s75, s44
	v_lshl_add_u64 v[176:177], v[176:177], 0, s[4:5]
	s_barrier
	s_cbranch_scc1 .LBB0_1992
	v_cmp_lt_i32_e32 vcc, v218, v212
	s_lshl_b64 s[4:5], s[22:23], 12
	s_add_u32 s4, s60, s4
	v_cndmask_b32_e32 v66, v211, v218, vcc
	v_lshlrev_b32_e32 v66, 2, v66
	ds_bpermute_b32 v66, v66, v187
	s_addc_u32 s5, s61, s5
	s_lshl_b32 s8, s50, 8
	s_add_u32 s4, s4, s8
	v_mov_b32_e32 v0, v204
	s_waitcnt lgkmcnt(0)
	v_add_f32_e32 v66, v187, v66
	v_div_scale_f32 v67, s[8:9], v66, v66, 1.0
	v_rcp_f32_e32 v68, v67
	s_addc_u32 s5, s5, 0
	s_add_i32 s21, s21, s94
	v_fma_f32 v69, -v67, v68, 1.0
	v_fmac_f32_e32 v68, v69, v68
	v_div_scale_f32 v69, vcc, 1.0, v66, 1.0
	v_mul_f32_e32 v70, v69, v68
	v_fma_f32 v71, -v67, v70, v69
	v_fmac_f32_e32 v70, v71, v68
	v_fma_f32 v67, -v67, v70, v69
	v_div_fmas_f32 v67, v67, v68, v70
	v_div_fixup_f32 v68, v67, v66, 1.0
	v_and_or_b32 v66, v0, 31, s47
	v_ashrrev_i32_e32 v67, 31, v66
	v_lshlrev_b64 v[66:67], 12, v[66:67]
	v_lshrrev_b32_e32 v0, 2, v0
	v_lshl_add_u64 v[66:67], s[4:5], 0, v[66:67]
	v_and_b32_e32 v0, 8, v0
	v_lshl_add_u64 v[66:67], v[66:67], 0, v[0:1]
	v_lshl_add_u64 v[66:67], v[66:67], 0, v[0:1]
	v_mul_f32_e32 v0, v50, v68
	v_mul_f32_e32 v50, v51, v68
	v_cvt_pk_bf16_f32 v50, v0, v50
	v_mul_f32_e32 v0, v52, v68
	v_mul_f32_e32 v51, v53, v68
	v_cvt_pk_bf16_f32 v51, v0, v51
	v_mul_f32_e32 v0, v54, v68
	v_mul_f32_e32 v52, v55, v68
	v_cvt_pk_bf16_f32 v52, v0, v52
	v_mul_f32_e32 v0, v56, v68
	v_mul_f32_e32 v53, v57, v68
	v_cvt_pk_bf16_f32 v53, v0, v53
	s_nop 1
	v_permlane32_swap_b32_e32 v50, v52
	v_permlane32_swap_b32_e32 v51, v53
	global_store_dwordx4 v[66:67], v[50:53], off
	v_mul_f32_e32 v0, v58, v68
	v_mul_f32_e32 v58, v59, v68
	v_cvt_pk_bf16_f32 v58, v0, v58
	v_mul_f32_e32 v0, v60, v68
	v_mul_f32_e32 v59, v61, v68
	v_cvt_pk_bf16_f32 v59, v0, v59
	v_mul_f32_e32 v0, v62, v68
	v_mul_f32_e32 v60, v63, v68
	v_cvt_pk_bf16_f32 v60, v0, v60
	v_mul_f32_e32 v0, v64, v68
	v_mul_f32_e32 v61, v65, v68
	v_cvt_pk_bf16_f32 v61, v0, v61
	s_nop 1
	v_permlane32_swap_b32_e32 v58, v60
	v_permlane32_swap_b32_e32 v59, v61
	global_store_dwordx4 v[66:67], v[58:61], off offset:32
	v_mul_f32_e32 v0, v34, v68
	v_mul_f32_e32 v34, v35, v68
	v_cvt_pk_bf16_f32 v34, v0, v34
	v_mul_f32_e32 v0, v36, v68
	v_mul_f32_e32 v35, v37, v68
	v_cvt_pk_bf16_f32 v35, v0, v35
	v_mul_f32_e32 v0, v38, v68
	v_mul_f32_e32 v36, v39, v68
	v_cvt_pk_bf16_f32 v36, v0, v36
	v_mul_f32_e32 v0, v40, v68
	v_mul_f32_e32 v37, v41, v68
	v_cvt_pk_bf16_f32 v37, v0, v37
	s_nop 1
	v_permlane32_swap_b32_e32 v34, v36
	v_permlane32_swap_b32_e32 v35, v37
	global_store_dwordx4 v[66:67], v[34:37], off offset:64
	v_mul_f32_e32 v0, v42, v68
	v_mul_f32_e32 v42, v43, v68
	v_cvt_pk_bf16_f32 v42, v0, v42
	v_mul_f32_e32 v0, v44, v68
	v_mul_f32_e32 v43, v45, v68
	v_cvt_pk_bf16_f32 v43, v0, v43
	v_mul_f32_e32 v0, v46, v68
	v_mul_f32_e32 v44, v47, v68
	v_cvt_pk_bf16_f32 v44, v0, v44
	v_mul_f32_e32 v0, v48, v68
	v_mul_f32_e32 v45, v49, v68
	v_cvt_pk_bf16_f32 v45, v0, v45
	s_nop 1
	v_permlane32_swap_b32_e32 v42, v44
	v_permlane32_swap_b32_e32 v43, v45
	global_store_dwordx4 v[66:67], v[42:45], off offset:96
	v_mul_f32_e32 v0, v18, v68
	v_mul_f32_e32 v18, v19, v68
	v_cvt_pk_bf16_f32 v18, v0, v18
	v_mul_f32_e32 v0, v20, v68
	v_mul_f32_e32 v19, v21, v68
	v_cvt_pk_bf16_f32 v19, v0, v19
	v_mul_f32_e32 v0, v22, v68
	v_mul_f32_e32 v20, v23, v68
	v_cvt_pk_bf16_f32 v20, v0, v20
	v_mul_f32_e32 v0, v24, v68
	v_mul_f32_e32 v21, v25, v68
	v_cvt_pk_bf16_f32 v21, v0, v21
	s_nop 1
	v_permlane32_swap_b32_e32 v18, v20
	v_permlane32_swap_b32_e32 v19, v21
	global_store_dwordx4 v[66:67], v[18:21], off offset:128
	v_mul_f32_e32 v0, v26, v68
	v_mul_f32_e32 v26, v27, v68
	v_cvt_pk_bf16_f32 v26, v0, v26
	v_mul_f32_e32 v0, v28, v68
	v_mul_f32_e32 v27, v29, v68
	v_cvt_pk_bf16_f32 v27, v0, v27
	v_mul_f32_e32 v0, v30, v68
	v_mul_f32_e32 v28, v31, v68
	v_cvt_pk_bf16_f32 v28, v0, v28
	v_mul_f32_e32 v0, v32, v68
	v_mul_f32_e32 v29, v33, v68
	v_cvt_pk_bf16_f32 v29, v0, v29
	v_readlane_b32 s4, v255, 42
	s_nop 1
	v_permlane32_swap_b32_e32 v26, v28
	v_permlane32_swap_b32_e32 v27, v29
	global_store_dwordx4 v[66:67], v[26:29], off offset:160
	v_mul_f32_e32 v0, v2, v68
	v_mul_f32_e32 v2, v3, v68
	v_cvt_pk_bf16_f32 v2, v0, v2
	v_mul_f32_e32 v0, v4, v68
	v_mul_f32_e32 v3, v5, v68
	v_cvt_pk_bf16_f32 v3, v0, v3
	v_mul_f32_e32 v0, v6, v68
	v_mul_f32_e32 v4, v7, v68
	v_cvt_pk_bf16_f32 v4, v0, v4
	v_mul_f32_e32 v0, v8, v68
	v_mul_f32_e32 v5, v9, v68
	v_cvt_pk_bf16_f32 v5, v0, v5
	s_add_i32 s16, s16, s4
	s_cmpk_lt_i32 s21, 0x400
	s_nop 1
	v_permlane32_swap_b32_e32 v2, v4
	v_permlane32_swap_b32_e32 v3, v5
	global_store_dwordx4 v[66:67], v[2:5], off offset:192
	v_mul_f32_e32 v0, v10, v68
	v_mul_f32_e32 v10, v11, v68
	v_cvt_pk_bf16_f32 v10, v0, v10
	v_mul_f32_e32 v0, v12, v68
	v_mul_f32_e32 v11, v13, v68
	v_cvt_pk_bf16_f32 v11, v0, v11
	v_mul_f32_e32 v0, v14, v68
	v_mul_f32_e32 v12, v15, v68
	v_cvt_pk_bf16_f32 v12, v0, v12
	v_mul_f32_e32 v0, v16, v68
	v_mul_f32_e32 v13, v17, v68
	v_cvt_pk_bf16_f32 v13, v0, v13
	s_nop 1
	v_permlane32_swap_b32_e32 v10, v12
	v_permlane32_swap_b32_e32 v11, v13
	global_store_dwordx4 v[66:67], v[10:13], off offset:224
	s_cbranch_scc1 .LBB0_1973
